# same as previous plus one 4-byte pad after the diff loop so that all later code keeps the byte placement of the best version
# speedup vs baseline: 1.0068x; 1.0049x over previous
; __device__ __forceinline__ float sum_x32(float v) { auto rr = __builtin_amdgcn_permlane32_swap(__float_as_uint(v), __float_as_uint(v), false, false); return __uint_as_float(rr[0]) + __uint_as_float(rr[1]); }
; DI void diff_unit(unsigned char* smem, const bf16* __restrict__ QKV, bf16* __restrict__ Y, int h, int qb, float lam, float outscale, const float* __restrict__ gain, float kn0, float kn1, int tid) {
;     ...
;     const float l_tot = sum_x32(l_run);
;     float* XG = (float*)smem + (map + 2 * qsub) * (66 * 64);
;     if (kvg == 1) {
;         XG[lane] = m_run; XG[64 + lane] = l_tot;
; #pragma unroll
;         for (int dt = 0; dt < 4; ++dt)
; #pragma unroll
;             for (int r = 0; r < 16; ++r) XG[(2 + dt * 16 + r) * 64 + lane] = o[dt][r];
;     }
.LBB0_224:
	s_or_b64 exec, exec, s[42:43]
	s_nop 0
	s_lshl_b32 s6, s60, 1
	s_or_b32 s6, s6, s62
	v_mov_b32_e32 v32, v162
	s_mulk_i32 s6, 0x4200
	s_nop 0
	v_permlane32_swap_b32_e32 v162, v32
	s_add_i32 s6, s6, 0
	v_add_f32_e32 v36, v162, v32
	s_cmp_lg_u32 s61, 1
	v_lshl_add_u32 v38, v47, 2, s6
	s_cbranch_scc1 .LBB0_226
	ds_write2st64_b32 v38, v163, v36 offset1:1
	ds_write2st64_b32 v38, v64, v65 offset0:2 offset1:3
	ds_write2st64_b32 v38, v66, v67 offset0:4 offset1:5
	ds_write2st64_b32 v38, v68, v69 offset0:6 offset1:7
	ds_write2st64_b32 v38, v70, v71 offset0:8 offset1:9
	ds_write2st64_b32 v38, v72, v73 offset0:10 offset1:11
	ds_write2st64_b32 v38, v74, v75 offset0:12 offset1:13
	ds_write2st64_b32 v38, v76, v77 offset0:14 offset1:15
	ds_write2st64_b32 v38, v78, v79 offset0:16 offset1:17
	ds_write2st64_b32 v38, v48, v49 offset0:18 offset1:19
	ds_write2st64_b32 v38, v50, v51 offset0:20 offset1:21
	ds_write2st64_b32 v38, v52, v53 offset0:22 offset1:23
	ds_write2st64_b32 v38, v54, v55 offset0:24 offset1:25
	ds_write2st64_b32 v38, v56, v57 offset0:26 offset1:27
	ds_write2st64_b32 v38, v58, v59 offset0:28 offset1:29
	ds_write2st64_b32 v38, v60, v61 offset0:30 offset1:31
	ds_write2st64_b32 v38, v62, v63 offset0:32 offset1:33
	ds_write2st64_b32 v38, v16, v17 offset0:34 offset1:35
	ds_write2st64_b32 v38, v18, v19 offset0:36 offset1:37
	ds_write2st64_b32 v38, v20, v21 offset0:38 offset1:39
	ds_write2st64_b32 v38, v22, v23 offset0:40 offset1:41
	ds_write2st64_b32 v38, v24, v25 offset0:42 offset1:43
	ds_write2st64_b32 v38, v26, v27 offset0:44 offset1:45
	ds_write2st64_b32 v38, v28, v29 offset0:46 offset1:47
	ds_write2st64_b32 v38, v30, v31 offset0:48 offset1:49
	ds_write2st64_b32 v38, v0, v1 offset0:50 offset1:51
	ds_write2st64_b32 v38, v2, v3 offset0:52 offset1:53
	ds_write2st64_b32 v38, v4, v5 offset0:54 offset1:55
	ds_write2st64_b32 v38, v6, v7 offset0:56 offset1:57
	ds_write2st64_b32 v38, v8, v9 offset0:58 offset1:59
	ds_write2st64_b32 v38, v10, v11 offset0:60 offset1:61
	ds_write2st64_b32 v38, v12, v13 offset0:62 offset1:63
	ds_write2st64_b32 v38, v14, v15 offset0:64 offset1:65
